# diff fast loop: next-tile DMA address SALU moved into the QK MFMA gaps (T phase only sets m0 and issues the 4 DMAs); NA cross-half max via permlane32_swap
# speedup vs baseline: 1.0062x; 1.0062x over previous
.LBB0_457:
	v_readlane_b32 s2, v254, 36
	s_add_i32 s7, s6, s2
	s_cmpk_gt_i32 s7, 0x7ff
	s_mov_b64 s[4:5], -1
	s_cbranch_scc1 .LBB0_456
	v_readlane_b32 s2, v253, 51
	v_readlane_b32 s4, v253, 49
	s_add_i32 s8, s6, s2
	s_ashr_i32 s9, s7, 5
	v_readlane_b32 s5, v253, 50
	s_and_b64 s[4:5], s[4:5], exec
	s_cselect_b32 s4, s85, s7
	s_cselect_b32 s5, s8, s9
	s_lshl_b32 s4, s4, 7
	s_and_b32 s16, s4, 0xf80
	s_lshl_b32 s4, s5, 7
	s_ashr_i32 s7, s5, 3
	s_and_b32 s8, s4, 0x380
	s_lshl_b32 s9, s7, 12
	s_lshl_b32 s10, s7, 8
	s_lshr_b32 s7, s8, 6
	s_add_i32 s10, s10, 0x8000
	s_mul_i32 s11, s7, 0x8800
	s_ashr_i32 s17, s9, 31
	v_mbcnt_lo_u32_b32 v0, -1, 0
	v_mbcnt_hi_u32_b32 v0, -1, v0
	s_add_u32 s4, s11, s9
	v_add_u32_e32 v187, s69, v0
	s_addc_u32 s5, 0, s17
	v_and_b32_e32 v0, 7, v187
	v_bfe_u32 v188, v187, 4, 2
	v_bitop3_b32 v0, v188, v0, s83 bitop3:0x36
	s_lshl_b64 s[4:5], s[4:5], 7
	v_and_or_b32 v0, v187, 56, v0
	s_add_u32 s12, s95, s4
	v_lshl_or_b32 v212, v0, 4, s46
	s_addc_u32 s13, s3, s5
	s_mov_b32 s19, m0
	s_mov_b32 m0, s23
	s_nop 0
	global_load_lds_dwordx4 v212, s[12:13]
	s_mov_b32 m0, s19
	s_add_i32 s12, s11, 0x8800
	s_add_u32 s28, s12, s9
	s_addc_u32 s29, 0, s17
	s_lshl_b64 s[28:29], s[28:29], 7
	v_bfe_u32 v5, v187, 5, 1
	v_lshlrev_b32_e32 v190, 4, v187
	s_add_u32 s28, s95, s28
	v_or_b32_e32 v2, s25, v5
	v_and_b32_e32 v3, 0x1c0, v190
	v_lshlrev_b32_e32 v189, 3, v187
	s_addc_u32 s29, s3, s29
	s_add_i32 s13, s23, 0x2000
	v_lshl_or_b32 v2, v2, 9, v3
	v_and_b32_e32 v6, 24, v189
	v_readlane_b32 s2, v253, 62
	s_add_u32 s4, s14, s4
	s_mov_b32 s17, m0
	s_mov_b32 m0, s13
	s_nop 0
	global_load_lds_dwordx4 v212, s[28:29]
	s_mov_b32 m0, s17
	s_addc_u32 s5, s15, s5
	v_or3_b32 v2, v2, s2, v6
	v_readlane_b32 s2, v253, 63
	s_add_i32 s13, s23, 0x4000
	v_and_b32_e32 v191, 31, v187
	v_add_lshl_u32 v222, v2, s2, 1
	s_mov_b32 s17, m0
	s_mov_b32 m0, s13
	s_nop 0
	global_load_lds_dwordx4 v222, s[4:5]
	s_mov_b32 m0, s17
	v_readlane_b32 s2, v254, 26
	s_add_i32 s13, s23, 0x6000
	v_lshlrev_b32_e32 v0, 4, v5
	v_add_lshl_u32 v223, v2, s2, 1
	s_mov_b32 s17, m0
	s_mov_b32 m0, s13
	s_nop 0
	global_load_lds_dwordx4 v223, s[4:5]
	s_mov_b32 m0, s17
	s_or_b32 s13, s9, 64
	s_ashr_i32 s17, s13, 31
	s_add_u32 s4, s11, s13
	s_addc_u32 s5, 0, s17
	s_lshl_b64 s[4:5], s[4:5], 7
	s_add_u32 s28, s95, s4
	s_addc_u32 s29, s3, s5
	s_add_i32 s19, s23, 0x8000
	s_mov_b32 s20, m0
	s_mov_b32 m0, s19
	s_nop 0
	global_load_lds_dwordx4 v212, s[28:29]
	s_mov_b32 m0, s20
	s_add_u32 s28, s12, s13
	s_addc_u32 s29, 0, s17
	s_lshl_b64 s[28:29], s[28:29], 7
	s_add_u32 s28, s95, s28
	s_addc_u32 s29, s3, s29
	s_add_i32 s13, s23, 0xa000
	s_mov_b32 s17, m0
	s_mov_b32 m0, s13
	s_nop 0
	global_load_lds_dwordx4 v212, s[28:29]
	s_mov_b32 m0, s17
	s_add_u32 s4, s14, s4
	s_addc_u32 s5, s15, s5
	s_add_i32 s13, s23, 0xc000
	s_mov_b32 s17, m0
	s_mov_b32 m0, s13
	s_nop 0
	global_load_lds_dwordx4 v222, s[4:5]
	s_mov_b32 m0, s17
	v_readlane_b32 s2, v254, 33
	s_add_i32 s13, s23, 0xe000
	s_mov_b32 s17, m0
	s_mov_b32 m0, s13
	s_nop 0
	global_load_lds_dwordx4 v223, s[4:5]
	s_mov_b32 m0, s17
	s_add_i32 s4, s7, s2
	v_readlane_b32 s2, v253, 53
	s_or_b32 s5, s16, s2
	s_or_b32 s7, s5, s9
	v_or_b32_e32 v2, s7, v191
	v_ashrrev_i32_e32 v3, 31, v2
	v_mad_u64_u32 v[2:3], s[4:5], s4, v217, v[2:3]
	v_lshlrev_b64 v[2:3], 7, v[2:3]
	v_lshl_add_u64 v[2:3], s[58:59], 0, v[2:3]
	v_lshl_add_u64 v[2:3], v[2:3], 0, v[0:1]
	global_load_dwordx4 v[144:147], v[2:3], off offset:96
	global_load_dwordx4 v[148:151], v[2:3], off offset:64
	global_load_dwordx4 v[152:155], v[2:3], off offset:32
	global_load_dwordx4 v[156:159], v[2:3], off
	v_lshrrev_b32_e32 v0, 1, v187
	v_lshrrev_b32_e32 v7, 2, v187
	v_lshlrev_b32_e32 v193, 2, v5
	v_lshlrev_b32_e32 v8, 1, v187
	v_bfe_u32 v9, v187, 1, 3
	v_bitop3_b32 v0, v5, v0, 7 bitop3:0x78
	v_and_or_b32 v7, v7, 3, v193
	v_lshlrev_b32_e32 v192, 3, v5
	v_and_b32_e32 v8, 32, v8
	v_bitop3_b32 v10, v5, v9, 2 bitop3:0x36
	v_bitop3_b32 v11, v5, v9, 4 bitop3:0x36
	v_bitop3_b32 v5, v5, v9, 6 bitop3:0x36
	v_lshlrev_b32_e32 v228, 4, v0
	v_lshlrev_b32_e32 v0, 6, v7
	v_mov_b32_e32 v14, v1
	v_mov_b32_e32 v15, v1
	v_mov_b32_e32 v2, v1
	v_mov_b32_e32 v3, v1
	v_mov_b32_e32 v4, v1
	v_lshlrev_b32_e32 v226, 4, v10
	v_lshlrev_b32_e32 v225, 4, v11
	v_lshlrev_b32_e32 v224, 4, v5
	v_or3_b32 v210, v0, v8, v6
	v_mov_b32_e32 v0, v1
	v_mov_b32_e32 v5, v1
	v_mov_b32_e32 v6, v1
	v_mov_b32_e32 v7, v1
	v_mov_b32_e32 v8, v1
	v_mov_b32_e32 v9, v1
	v_mov_b32_e32 v10, v1
	v_mov_b32_e32 v11, v1
	v_mov_b32_e32 v12, v1
	v_mov_b32_e32 v13, v1
	v_mov_b64_e32 v[78:79], v[14:15]
	v_mov_b64_e32 v[62:63], v[14:15]
	v_mov_b64_e32 v[46:47], v[14:15]
	v_mov_b64_e32 v[30:31], v[14:15]
	v_mov_b64_e32 v[94:95], v[14:15]
	s_mov_b32 s13, 2
	s_mov_b32 s19, 0
	v_and_b32_e32 v194, 63, v187
	v_lshl_add_u32 v227, v191, 7, s21
	v_add_u32_e32 v195, 0, v210
	s_mov_b64 s[4:5], -1
	v_mov_b32_e32 v209, 0
	v_mov_b32_e32 v140, 0
	v_mov_b32_e32 v141, 0
	v_mov_b32_e32 v142, 0
	v_mov_b32_e32 v143, 0
	v_mov_b32_e32 v136, 0
	v_mov_b32_e32 v137, 0
	v_mov_b32_e32 v138, 0
	v_mov_b32_e32 v139, 0
	v_mov_b32_e32 v132, 0
	v_mov_b32_e32 v133, 0
	v_mov_b32_e32 v134, 0
	v_mov_b32_e32 v135, 0
	v_mov_b32_e32 v128, 0
	v_mov_b32_e32 v129, 0
	v_mov_b32_e32 v130, 0
	v_mov_b32_e32 v131, 0
	v_mov_b64_e32 v[76:77], v[12:13]
	v_mov_b64_e32 v[74:75], v[10:11]
	v_mov_b64_e32 v[72:73], v[8:9]
	v_mov_b64_e32 v[70:71], v[6:7]
	v_mov_b64_e32 v[68:69], v[4:5]
	v_mov_b64_e32 v[66:67], v[2:3]
	v_mov_b64_e32 v[64:65], v[0:1]
	v_mov_b64_e32 v[60:61], v[12:13]
	v_mov_b64_e32 v[58:59], v[10:11]
	v_mov_b64_e32 v[56:57], v[8:9]
	v_mov_b64_e32 v[54:55], v[6:7]
	v_mov_b64_e32 v[52:53], v[4:5]
	v_mov_b64_e32 v[50:51], v[2:3]
	v_mov_b64_e32 v[48:49], v[0:1]
	v_mov_b64_e32 v[44:45], v[12:13]
	v_mov_b64_e32 v[42:43], v[10:11]
	v_mov_b64_e32 v[40:41], v[8:9]
	v_mov_b64_e32 v[38:39], v[6:7]
	v_mov_b64_e32 v[36:37], v[4:5]
	v_mov_b64_e32 v[34:35], v[2:3]
	v_mov_b64_e32 v[32:33], v[0:1]
	v_mov_b64_e32 v[28:29], v[12:13]
	v_mov_b64_e32 v[26:27], v[10:11]
	v_mov_b64_e32 v[24:25], v[8:9]
	v_mov_b64_e32 v[22:23], v[6:7]
	v_mov_b64_e32 v[20:21], v[4:5]
	v_mov_b64_e32 v[18:19], v[2:3]
	v_mov_b64_e32 v[16:17], v[0:1]
	v_mov_b64_e32 v[92:93], v[12:13]
	v_mov_b64_e32 v[90:91], v[10:11]
	v_mov_b64_e32 v[88:89], v[8:9]
	v_mov_b64_e32 v[86:87], v[6:7]
	v_mov_b64_e32 v[84:85], v[4:5]
	v_mov_b64_e32 v[82:83], v[2:3]
	v_mov_b64_e32 v[80:81], v[0:1]
	s_mov_b32 s28, 0
	s_waitcnt vmcnt(0)
	v_mov_b32_e32 v218, s60
	v_mov_b32_e32 v219, s60
	v_mov_b32_e32 v220, s60
	v_mov_b32_e32 v221, s60
	s_add_i32 s20, s19, 0x10000
	s_and_b32 s20, s20, 0x18000
	s_add_i32 s20, s20, s23
	s_add_i32 s62, s13, -2
	s_cmpk_gt_u32 s62, 0x41
	s_cselect_b32 s61, 1, 0
	s_cmp_lt_u32 s62, 62
	s_cselect_b32 s16, 0, 0xffffffc0
	s_cselect_b32 s17, s9, s10
	s_add_i32 s16, s16, s13
	s_lshl_b32 s16, s16, 6
	s_add_i32 s62, s16, s17
	s_ashr_i32 s63, s62, 31
	s_add_u32 s30, s62, s11
	s_addc_u32 s31, s63, 0
	s_lshl_b64 s[30:31], s[30:31], 7
	s_add_u32 s34, s95, s30
	s_addc_u32 s35, s3, s31
	s_add_u32 s16, s62, s12
	s_addc_u32 s17, s63, 0
	s_lshl_b64 s[16:17], s[16:17], 7
	s_add_u32 s16, s95, s16
	s_addc_u32 s17, s3, s17
	s_add_u32 s30, s14, s30
	s_addc_u32 s31, s15, s31
	s_branch .Lf_460

.Lf_459:
	v_mov_b32_e32 v180, v128
	v_mov_b32_e32 v181, v129
	v_mov_b32_e32 v182, v130
	v_mov_b32_e32 v183, v131
	v_mfma_f32_32x32x16_bf16 v[64:79], v[176:179], v[140:143], v[64:79]
	ds_read_b64_tr_b16 v[128:129], v0 offset:24576
	ds_read_b64_tr_b16 v[130:131], v0 offset:25088
	v_exp_f32_e32 v14, v112
	v_mfma_f32_32x32x16_bf16 v[64:79], v[172:175], v[136:139], v[64:79]
	ds_read_b64_tr_b16 v[172:173], v0 offset:25600
	ds_read_b64_tr_b16 v[174:175], v0 offset:26112
	v_exp_f32_e32 v15, v96
	v_mfma_f32_32x32x16_bf16 v[64:79], v[168:171], v[132:135], v[64:79]
	ds_read_b64_tr_b16 v[168:169], v0 offset:26624
	ds_read_b64_tr_b16 v[170:171], v0 offset:27136
	v_exp_f32_e32 v96, v113
	v_mfma_f32_32x32x16_bf16 v[64:79], v[164:167], v[180:183], v[64:79]
	ds_read_b64_tr_b16 v[164:165], v0 offset:27648
	ds_read_b64_tr_b16 v[166:167], v0 offset:28160
	v_exp_f32_e32 v97, v97
	v_mfma_f32_32x32x16_bf16 v[48:63], v[160:163], v[140:143], v[48:63]
	ds_read_b64_tr_b16 v[160:161], v0 offset:28672
	ds_read_b64_tr_b16 v[162:163], v0 offset:29184
	v_exp_f32_e32 v112, v114
	v_mfma_f32_32x32x16_bf16 v[48:63], v[10:13], v[136:139], v[48:63]
	ds_read_b64_tr_b16 v[10:11], v0 offset:29696
	ds_read_b64_tr_b16 v[12:13], v0 offset:30208
	v_exp_f32_e32 v98, v98
	v_mfma_f32_32x32x16_bf16 v[48:63], v[6:9], v[132:135], v[48:63]
	ds_read_b64_tr_b16 v[6:7], v0 offset:30720
	ds_read_b64_tr_b16 v[8:9], v0 offset:31232
	v_exp_f32_e32 v113, v115
	v_mfma_f32_32x32x16_bf16 v[48:63], v[2:5], v[180:183], v[48:63]
	ds_read_b64_tr_b16 v[2:3], v0 offset:31744
	ds_read_b64_tr_b16 v[4:5], v0 offset:32256
	v_exp_f32_e32 v0, v99
	s_waitcnt lgkmcnt(14)
	v_mfma_f32_32x32x16_bf16 v[32:47], v[128:131], v[140:143], v[32:47]
	v_exp_f32_e32 v99, v116
	v_exp_f32_e32 v100, v100
	v_exp_f32_e32 v114, v117
	s_waitcnt lgkmcnt(12)
	v_mfma_f32_32x32x16_bf16 v[32:47], v[172:175], v[136:139], v[32:47]
	v_exp_f32_e32 v101, v101
	v_exp_f32_e32 v115, v118
	v_exp_f32_e32 v102, v102
	s_waitcnt lgkmcnt(10)
	v_mfma_f32_32x32x16_bf16 v[32:47], v[168:171], v[132:135], v[32:47]
	v_exp_f32_e32 v116, v119
	v_exp_f32_e32 v103, v103
	v_exp_f32_e32 v117, v120
	s_waitcnt lgkmcnt(8)
	v_mfma_f32_32x32x16_bf16 v[32:47], v[164:167], v[180:183], v[32:47]
	v_exp_f32_e32 v104, v104
	v_exp_f32_e32 v118, v121
	v_exp_f32_e32 v105, v105
	s_waitcnt lgkmcnt(6)
	v_mfma_f32_32x32x16_bf16 v[16:31], v[160:163], v[140:143], v[16:31]
	v_exp_f32_e32 v119, v122
	v_exp_f32_e32 v106, v106
	v_exp_f32_e32 v120, v123
	s_waitcnt lgkmcnt(4)
	v_mfma_f32_32x32x16_bf16 v[16:31], v[10:13], v[136:139], v[16:31]
	v_exp_f32_e32 v10, v107
	v_exp_f32_e32 v11, v124
	v_exp_f32_e32 v12, v108
	s_waitcnt lgkmcnt(2)
	v_mfma_f32_32x32x16_bf16 v[16:31], v[6:9], v[132:135], v[16:31]
	v_exp_f32_e32 v6, v125
	v_exp_f32_e32 v7, v109
	v_exp_f32_e32 v8, v126
	s_waitcnt lgkmcnt(0)
	v_mfma_f32_32x32x16_bf16 v[16:31], v[2:5], v[180:183], v[16:31]
	v_exp_f32_e32 v107, v110
	s_nop 0
	v_mfma_f32_32x32x16_bf16 v[80:95], v[218:221], v[140:143], v[80:95]
	v_exp_f32_e32 v108, v127
	v_exp_f32_e32 v109, v111
	v_cvt_pk_bf16_f32 v140, v14, v96
	v_cvt_pk_bf16_f32 v143, v115, v116
	v_mfma_f32_32x32x16_bf16 v[80:95], v[218:221], v[136:139], v[80:95]
	v_cvt_pk_bf16_f32 v128, v104, v105
	v_cvt_pk_bf16_f32 v141, v112, v113
	v_cvt_pk_bf16_f32 v136, v117, v118
	v_mfma_f32_32x32x16_bf16 v[80:95], v[218:221], v[132:135], v[80:95]
	v_cvt_pk_bf16_f32 v137, v119, v120
	v_cvt_pk_bf16_f32 v129, v106, v10
	v_cvt_pk_bf16_f32 v132, v15, v97
	v_cvt_pk_bf16_f32 v130, v12, v7
	v_cvt_pk_bf16_f32 v138, v11, v6
	v_cvt_pk_bf16_f32 v133, v98, v0
	v_cvt_pk_bf16_f32 v142, v99, v114
	v_cvt_pk_bf16_f32 v134, v100, v101
	v_cvt_pk_bf16_f32 v135, v102, v103
	v_cvt_pk_bf16_f32 v139, v8, v108
	v_cvt_pk_bf16_f32 v131, v107, v109
	v_mfma_f32_32x32x16_bf16 v[80:95], v[218:221], v[180:183], v[80:95]
	s_add_i32 s28, s28, 1
	s_add_i32 s13, s13, 1
	s_add_i32 s19, s19, 0x8000
	s_cmpk_eq_i32 s13, 0x45
	s_cbranch_scc1 .LBB0_464
.Lf_460:
	s_waitcnt vmcnt(4) lgkmcnt(0)
	s_barrier
	s_cmp_lg_u32 s61, 0
	s_cbranch_scc1 .Lf_462
	s_mov_b32 s22, m0
	s_mov_b32 m0, s20
	s_nop 0
	global_load_lds_dwordx4 v212, s[34:35]
	s_mov_b32 m0, s22
	s_add_i32 s63, s20, 0x2000
	s_mov_b32 s22, m0
	s_mov_b32 m0, s63
	s_nop 0
	global_load_lds_dwordx4 v212, s[16:17]
	s_mov_b32 m0, s22
	s_add_i32 s63, s20, 0x4000
	s_mov_b32 s22, m0
	s_mov_b32 m0, s63
	s_nop 0
	global_load_lds_dwordx4 v222, s[30:31]
	s_mov_b32 m0, s22
	s_add_i32 s63, s20, 0x6000
	s_mov_b32 s22, m0
	s_mov_b32 m0, s63
	s_nop 0
	global_load_lds_dwordx4 v223, s[30:31]
	s_mov_b32 m0, s22
.Lf_462:
	s_and_b32 s17, s19, 0x18000
	v_add_u32_e32 v0, s17, v227
	v_add_u32_e32 v2, v0, v228
	ds_read_b128 v[96:99], v2
	ds_read_b128 v[100:103], v2 offset:4096
	v_add_u32_e32 v2, v0, v226
	ds_read_b128 v[180:183], v2
	ds_read_b128 v[230:233], v2 offset:4096
	v_add_u32_e32 v2, v0, v225
	v_add_u32_e32 v0, v0, v224
	s_min_u32 s16, s28, 1
	ds_read_b128 v[234:237], v2
	ds_read_b128 v[238:241], v2 offset:4096
	ds_read_b128 v[242:245], v0
	ds_read_b128 v[246:249], v0 offset:4096
	s_lshl_b32 s16, s16, 15
	s_sub_i32 s16, s19, s16
	s_and_b32 s16, s16, 0x18000
	v_add_u32_e32 v0, s16, v195
	s_setprio 1
	s_waitcnt lgkmcnt(6)
	v_mfma_f32_32x32x16_bf16 v[112:127], v[96:99], v[156:159], 0
	s_add_i32 s22, s13, 1
	s_add_i32 s61, s19, 0x8000
	s_add_i32 s20, s61, 0x10000
	s_and_b32 s20, s20, 0x18000
	v_mfma_f32_32x32x16_bf16 v[96:111], v[100:103], v[156:159], 0
	s_add_i32 s20, s20, s23
	s_add_i32 s62, s22, -2
	s_cmpk_gt_u32 s62, 0x41
	s_cselect_b32 s61, 1, 0
	s_waitcnt lgkmcnt(4)
	v_mfma_f32_32x32x16_bf16 v[112:127], v[180:183], v[152:155], v[112:127]
	s_cmp_lt_u32 s62, 62
	s_cselect_b32 s16, 0, 0xffffffc0
	s_cselect_b32 s17, s9, s10
	s_add_i32 s16, s16, s22
	v_mfma_f32_32x32x16_bf16 v[96:111], v[230:233], v[152:155], v[96:111]
	s_lshl_b32 s16, s16, 6
	s_add_i32 s62, s16, s17
	s_ashr_i32 s63, s62, 31
	s_add_u32 s30, s62, s11
	s_waitcnt lgkmcnt(2)
	v_mfma_f32_32x32x16_bf16 v[112:127], v[234:237], v[148:151], v[112:127]
	s_addc_u32 s31, s63, 0
	s_lshl_b64 s[30:31], s[30:31], 7
	s_add_u32 s34, s95, s30
	s_addc_u32 s35, s3, s31
	v_mfma_f32_32x32x16_bf16 v[96:111], v[238:241], v[148:151], v[96:111]
	s_add_u32 s16, s62, s12
	s_addc_u32 s17, s63, 0
	s_lshl_b64 s[16:17], s[16:17], 7
	s_add_u32 s16, s95, s16
	s_waitcnt lgkmcnt(0)
	v_mfma_f32_32x32x16_bf16 v[112:127], v[242:245], v[144:147], v[112:127]
	s_addc_u32 s17, s3, s17
	s_add_u32 s30, s14, s30
	s_addc_u32 s31, s15, s31
	v_mfma_f32_32x32x16_bf16 v[96:111], v[246:249], v[144:147], v[96:111]
	ds_read_b64_tr_b16 v[176:177], v0 offset:16384
	ds_read_b64_tr_b16 v[178:179], v0 offset:16896
	ds_read_b64_tr_b16 v[172:173], v0 offset:17408
	ds_read_b64_tr_b16 v[174:175], v0 offset:17920
	ds_read_b64_tr_b16 v[168:169], v0 offset:18432
	ds_read_b64_tr_b16 v[170:171], v0 offset:18944
	ds_read_b64_tr_b16 v[164:165], v0 offset:19456
	ds_read_b64_tr_b16 v[166:167], v0 offset:19968
	ds_read_b64_tr_b16 v[160:161], v0 offset:20480
	ds_read_b64_tr_b16 v[162:163], v0 offset:20992
	ds_read_b64_tr_b16 v[10:11], v0 offset:21504
	ds_read_b64_tr_b16 v[12:13], v0 offset:22016
	ds_read_b64_tr_b16 v[6:7], v0 offset:22528
	ds_read_b64_tr_b16 v[8:9], v0 offset:23040
	ds_read_b64_tr_b16 v[2:3], v0 offset:23552
	ds_read_b64_tr_b16 v[4:5], v0 offset:24064
	s_setprio 0
	v_max3_f32 v14, v112, v113, v114
	v_max3_f32 v15, v115, v116, v117
	v_max3_f32 v180, v118, v119, v120
	v_max3_f32 v181, v121, v122, v123
	v_max3_f32 v182, v124, v125, v126
	v_max3_f32 v183, v96, v97, v98
	v_max3_f32 v230, v99, v100, v101
	v_max3_f32 v231, v102, v103, v104
	s_nop 0
	v_max3_f32 v14, v14, v15, v180
	v_max3_f32 v232, v105, v106, v107
	v_max3_f32 v15, v181, v182, v127
	v_max3_f32 v233, v108, v109, v110
	v_max3_f32 v180, v183, v230, v231
	v_max3_f32 v181, v232, v233, v111
	s_nop 0
	v_max3_f32 v14, v14, v15, v180
	v_max_f32_e32 v14, v14, v181
	v_mov_b32_e32 v15, v14
	s_nop 1
	v_permlane32_swap_b32_e32 v15, v14
	v_max_f32_e32 v14, v14, v15
	v_cmp_lt_f32_e32 vcc, 0x42800000, v14
	s_waitcnt lgkmcnt(0)
	s_cbranch_vccz .Lf_459
	s_branch .Lf_to463
